# gemm_tail_res K-loop: 20 loads in flight with counted vmcnt instead of 4x(load,vmcnt0,mfma) per step
# baseline (speedup 1.0000x reference)
.Ltail_k_entry:
	v_lshl_add_u64 v[134:135], v[30:31], 0, v[20:21]
	v_lshl_add_u64 v[136:137], v[32:33], 0, v[20:21]
	v_lshl_add_u64 v[138:139], v[38:39], 0, v[20:21]
	v_lshl_add_u64 v[140:141], v[34:35], 0, v[20:21]
	v_lshl_add_u64 v[142:143], v[36:37], 0, v[20:21]
	s_cmp_eq_u32 s6, 0x80
	s_cbranch_scc1 .Ltail_k4
	global_load_dwordx4 v[54:57], v[134:135], off offset:0
	global_load_dwordx4 v[58:61], v[136:137], off offset:0
	global_load_dwordx4 v[62:65], v[138:139], off offset:0
	global_load_dwordx4 v[66:69], v[140:141], off offset:0
	global_load_dwordx4 v[70:73], v[142:143], off offset:0
	global_load_dwordx4 v[74:77], v[134:135], off offset:64
	global_load_dwordx4 v[78:81], v[136:137], off offset:64
	global_load_dwordx4 v[82:85], v[138:139], off offset:64
	global_load_dwordx4 v[86:89], v[140:141], off offset:64
	global_load_dwordx4 v[90:93], v[142:143], off offset:64
	global_load_dwordx4 v[94:97], v[134:135], off offset:128
	global_load_dwordx4 v[98:101], v[136:137], off offset:128
	global_load_dwordx4 v[102:105], v[138:139], off offset:128
	global_load_dwordx4 v[106:109], v[140:141], off offset:128
	global_load_dwordx4 v[110:113], v[142:143], off offset:128
	global_load_dwordx4 v[114:117], v[134:135], off offset:192
	global_load_dwordx4 v[118:121], v[136:137], off offset:192
	global_load_dwordx4 v[122:125], v[138:139], off offset:192
	global_load_dwordx4 v[126:129], v[140:141], off offset:192
	global_load_dwordx4 v[130:133], v[142:143], off offset:192
	s_waitcnt vmcnt(15)
	v_mfma_f32_16x16x32_bf16 v[4:7], v[54:57], v[58:61], v[4:7]
	v_mfma_f32_16x16x32_bf16 v[12:15], v[54:57], v[62:65], v[12:15]
	v_mfma_f32_16x16x32_bf16 v[8:11], v[54:57], v[66:69], v[8:11]
	v_mfma_f32_16x16x32_bf16 v[0:3], v[54:57], v[70:73], v[0:3]
	global_load_dwordx4 v[54:57], v[134:135], off offset:256
	global_load_dwordx4 v[58:61], v[136:137], off offset:256
	global_load_dwordx4 v[62:65], v[138:139], off offset:256
	global_load_dwordx4 v[66:69], v[140:141], off offset:256
	global_load_dwordx4 v[70:73], v[142:143], off offset:256
	s_waitcnt vmcnt(15)
	v_mfma_f32_16x16x32_bf16 v[4:7], v[74:77], v[78:81], v[4:7]
	v_mfma_f32_16x16x32_bf16 v[12:15], v[74:77], v[82:85], v[12:15]
	v_mfma_f32_16x16x32_bf16 v[8:11], v[74:77], v[86:89], v[8:11]
	v_mfma_f32_16x16x32_bf16 v[0:3], v[74:77], v[90:93], v[0:3]
	global_load_dwordx4 v[74:77], v[134:135], off offset:320
	global_load_dwordx4 v[78:81], v[136:137], off offset:320
	global_load_dwordx4 v[82:85], v[138:139], off offset:320
	global_load_dwordx4 v[86:89], v[140:141], off offset:320
	global_load_dwordx4 v[90:93], v[142:143], off offset:320
	s_waitcnt vmcnt(15)
	v_mfma_f32_16x16x32_bf16 v[4:7], v[94:97], v[98:101], v[4:7]
	v_mfma_f32_16x16x32_bf16 v[12:15], v[94:97], v[102:105], v[12:15]
	v_mfma_f32_16x16x32_bf16 v[8:11], v[94:97], v[106:109], v[8:11]
	v_mfma_f32_16x16x32_bf16 v[0:3], v[94:97], v[110:113], v[0:3]
	global_load_dwordx4 v[94:97], v[134:135], off offset:384
	global_load_dwordx4 v[98:101], v[136:137], off offset:384
	global_load_dwordx4 v[102:105], v[138:139], off offset:384
	global_load_dwordx4 v[106:109], v[140:141], off offset:384
	global_load_dwordx4 v[110:113], v[142:143], off offset:384
	s_waitcnt vmcnt(15)
	v_mfma_f32_16x16x32_bf16 v[4:7], v[114:117], v[118:121], v[4:7]
	v_mfma_f32_16x16x32_bf16 v[12:15], v[114:117], v[122:125], v[12:15]
	v_mfma_f32_16x16x32_bf16 v[8:11], v[114:117], v[126:129], v[8:11]
	v_mfma_f32_16x16x32_bf16 v[0:3], v[114:117], v[130:133], v[0:3]
	global_load_dwordx4 v[114:117], v[134:135], off offset:448
	global_load_dwordx4 v[118:121], v[136:137], off offset:448
	global_load_dwordx4 v[122:125], v[138:139], off offset:448
	global_load_dwordx4 v[126:129], v[140:141], off offset:448
	global_load_dwordx4 v[130:133], v[142:143], off offset:448
	s_waitcnt vmcnt(15)
	v_mfma_f32_16x16x32_bf16 v[4:7], v[54:57], v[58:61], v[4:7]
	v_mfma_f32_16x16x32_bf16 v[12:15], v[54:57], v[62:65], v[12:15]
	v_mfma_f32_16x16x32_bf16 v[8:11], v[54:57], v[66:69], v[8:11]
	v_mfma_f32_16x16x32_bf16 v[0:3], v[54:57], v[70:73], v[0:3]
	global_load_dwordx4 v[54:57], v[134:135], off offset:512
	global_load_dwordx4 v[58:61], v[136:137], off offset:512
	global_load_dwordx4 v[62:65], v[138:139], off offset:512
	global_load_dwordx4 v[66:69], v[140:141], off offset:512
	global_load_dwordx4 v[70:73], v[142:143], off offset:512
	s_waitcnt vmcnt(15)
	v_mfma_f32_16x16x32_bf16 v[4:7], v[74:77], v[78:81], v[4:7]
	v_mfma_f32_16x16x32_bf16 v[12:15], v[74:77], v[82:85], v[12:15]
	v_mfma_f32_16x16x32_bf16 v[8:11], v[74:77], v[86:89], v[8:11]
	v_mfma_f32_16x16x32_bf16 v[0:3], v[74:77], v[90:93], v[0:3]
	global_load_dwordx4 v[74:77], v[134:135], off offset:576
	global_load_dwordx4 v[78:81], v[136:137], off offset:576
	global_load_dwordx4 v[82:85], v[138:139], off offset:576
	global_load_dwordx4 v[86:89], v[140:141], off offset:576
	global_load_dwordx4 v[90:93], v[142:143], off offset:576
	s_waitcnt vmcnt(15)
	v_mfma_f32_16x16x32_bf16 v[4:7], v[94:97], v[98:101], v[4:7]
	v_mfma_f32_16x16x32_bf16 v[12:15], v[94:97], v[102:105], v[12:15]
	v_mfma_f32_16x16x32_bf16 v[8:11], v[94:97], v[106:109], v[8:11]
	v_mfma_f32_16x16x32_bf16 v[0:3], v[94:97], v[110:113], v[0:3]
	global_load_dwordx4 v[94:97], v[134:135], off offset:640
	global_load_dwordx4 v[98:101], v[136:137], off offset:640
	global_load_dwordx4 v[102:105], v[138:139], off offset:640
	global_load_dwordx4 v[106:109], v[140:141], off offset:640
	global_load_dwordx4 v[110:113], v[142:143], off offset:640
	s_waitcnt vmcnt(15)
	v_mfma_f32_16x16x32_bf16 v[4:7], v[114:117], v[118:121], v[4:7]
	v_mfma_f32_16x16x32_bf16 v[12:15], v[114:117], v[122:125], v[12:15]
	v_mfma_f32_16x16x32_bf16 v[8:11], v[114:117], v[126:129], v[8:11]
	v_mfma_f32_16x16x32_bf16 v[0:3], v[114:117], v[130:133], v[0:3]
	s_waitcnt vmcnt(10)
	v_mfma_f32_16x16x32_bf16 v[4:7], v[54:57], v[58:61], v[4:7]
	v_mfma_f32_16x16x32_bf16 v[12:15], v[54:57], v[62:65], v[12:15]
	v_mfma_f32_16x16x32_bf16 v[8:11], v[54:57], v[66:69], v[8:11]
	v_mfma_f32_16x16x32_bf16 v[0:3], v[54:57], v[70:73], v[0:3]
	s_waitcnt vmcnt(5)
	v_mfma_f32_16x16x32_bf16 v[4:7], v[74:77], v[78:81], v[4:7]
	v_mfma_f32_16x16x32_bf16 v[12:15], v[74:77], v[82:85], v[12:15]
	v_mfma_f32_16x16x32_bf16 v[8:11], v[74:77], v[86:89], v[8:11]
	v_mfma_f32_16x16x32_bf16 v[0:3], v[74:77], v[90:93], v[0:3]
	s_waitcnt vmcnt(0)
	v_mfma_f32_16x16x32_bf16 v[4:7], v[94:97], v[98:101], v[4:7]
	v_mfma_f32_16x16x32_bf16 v[12:15], v[94:97], v[102:105], v[12:15]
	v_mfma_f32_16x16x32_bf16 v[8:11], v[94:97], v[106:109], v[8:11]
	v_mfma_f32_16x16x32_bf16 v[0:3], v[94:97], v[110:113], v[0:3]
	s_branch .Ltail_done
.Ltail_k4:
	global_load_dwordx4 v[54:57], v[134:135], off offset:0
	global_load_dwordx4 v[58:61], v[136:137], off offset:0
	global_load_dwordx4 v[62:65], v[138:139], off offset:0
	global_load_dwordx4 v[66:69], v[140:141], off offset:0
	global_load_dwordx4 v[70:73], v[142:143], off offset:0
	global_load_dwordx4 v[74:77], v[134:135], off offset:64
	global_load_dwordx4 v[78:81], v[136:137], off offset:64
	global_load_dwordx4 v[82:85], v[138:139], off offset:64
	global_load_dwordx4 v[86:89], v[140:141], off offset:64
	global_load_dwordx4 v[90:93], v[142:143], off offset:64
	global_load_dwordx4 v[94:97], v[134:135], off offset:128
	global_load_dwordx4 v[98:101], v[136:137], off offset:128
	global_load_dwordx4 v[102:105], v[138:139], off offset:128
	global_load_dwordx4 v[106:109], v[140:141], off offset:128
	global_load_dwordx4 v[110:113], v[142:143], off offset:128
	global_load_dwordx4 v[114:117], v[134:135], off offset:192
	global_load_dwordx4 v[118:121], v[136:137], off offset:192
	global_load_dwordx4 v[122:125], v[138:139], off offset:192
	global_load_dwordx4 v[126:129], v[140:141], off offset:192
	global_load_dwordx4 v[130:133], v[142:143], off offset:192
	s_waitcnt vmcnt(15)
	v_mfma_f32_16x16x32_bf16 v[4:7], v[54:57], v[58:61], v[4:7]
	v_mfma_f32_16x16x32_bf16 v[12:15], v[54:57], v[62:65], v[12:15]
	v_mfma_f32_16x16x32_bf16 v[8:11], v[54:57], v[66:69], v[8:11]
	v_mfma_f32_16x16x32_bf16 v[0:3], v[54:57], v[70:73], v[0:3]
	s_waitcnt vmcnt(10)
	v_mfma_f32_16x16x32_bf16 v[4:7], v[74:77], v[78:81], v[4:7]
	v_mfma_f32_16x16x32_bf16 v[12:15], v[74:77], v[82:85], v[12:15]
	v_mfma_f32_16x16x32_bf16 v[8:11], v[74:77], v[86:89], v[8:11]
	v_mfma_f32_16x16x32_bf16 v[0:3], v[74:77], v[90:93], v[0:3]
	s_waitcnt vmcnt(5)
	v_mfma_f32_16x16x32_bf16 v[4:7], v[94:97], v[98:101], v[4:7]
	v_mfma_f32_16x16x32_bf16 v[12:15], v[94:97], v[102:105], v[12:15]
	v_mfma_f32_16x16x32_bf16 v[8:11], v[94:97], v[106:109], v[8:11]
	v_mfma_f32_16x16x32_bf16 v[0:3], v[94:97], v[110:113], v[0:3]
	s_waitcnt vmcnt(0)
	v_mfma_f32_16x16x32_bf16 v[4:7], v[114:117], v[118:121], v[4:7]
	v_mfma_f32_16x16x32_bf16 v[12:15], v[114:117], v[122:125], v[12:15]
	v_mfma_f32_16x16x32_bf16 v[8:11], v[114:117], v[126:129], v[8:11]
	v_mfma_f32_16x16x32_bf16 v[0:3], v[114:117], v[130:133], v[0:3]
.Ltail_done:
	s_nop 7
	s_addk_i32 s5, 0x4000
	ds_write2_b32 v40, v4, v12 offset1:16
	ds_write2_b32 v40, v5, v13 offset0:64 offset1:80
	ds_write2_b32 v40, v6, v14 offset0:128 offset1:144
	ds_write2_b32 v40, v7, v15 offset0:192 offset1:208
	s_nop 1
	ds_write2_b32 v40, v8, v0 offset0:32 offset1:48
	ds_write2_b32 v40, v9, v1 offset0:96 offset1:112
	ds_write2_b32 v40, v10, v2 offset0:160 offset1:176
	ds_write2_b32 v40, v11, v3 offset0:224 offset1:240
	v_add_u32_e32 v0, s5, v41
	v_ashrrev_i32_e32 v1, 31, v0
	v_lshlrev_b64 v[2:3], 10, v[0:1]
	v_or_b32_e32 v2, s4, v2
	v_or_b32_e32 v2, v2, v18
	v_lshlrev_b64 v[14:15], 1, v[2:3]
	v_lshl_add_u64 v[2:3], s[84:85], 0, v[14:15]
	s_waitcnt lgkmcnt(0)
	s_barrier
	global_load_dword v34, v[2:3], off
	ds_read2st64_b64 v[2:5], v42 offset1:8
	ds_read2st64_b64 v[6:9], v42 offset0:16 offset1:24
	ds_read2st64_b64 v[10:13], v42 offset0:32 offset1:40
	ds_read2st64_b64 v[30:33], v42 offset0:48 offset1:56
	s_waitcnt lgkmcnt(3)
	v_pk_add_f32 v[2:3], v[2:3], 0 op_sel_hi:[1,0]
	s_nop 0
	v_pk_add_f32 v[2:3], v[2:3], v[4:5]
	s_waitcnt vmcnt(0)
	v_lshlrev_b32_e32 v4, 16, v34
	s_waitcnt lgkmcnt(2)
	v_pk_add_f32 v[2:3], v[2:3], v[6:7]
	v_and_b32_e32 v5, 0xffff0000, v34
	v_pk_add_f32 v[2:3], v[2:3], v[8:9]
	s_waitcnt lgkmcnt(1)
	v_pk_add_f32 v[2:3], v[2:3], v[10:11]
	s_nop 0
	v_pk_add_f32 v[2:3], v[2:3], v[12:13]
	s_waitcnt lgkmcnt(0)
	v_pk_add_f32 v[2:3], v[2:3], v[30:31]
	s_nop 0
	v_pk_add_f32 v[2:3], v[2:3], v[32:33]
	s_nop 0
	v_pk_fma_f32 v[4:5], v[186:187], v[2:3], v[4:5]
	s_nop 0
	v_pk_mul_f32 v[2:3], v[4:5], v[4:5]
	v_cvt_pk_bf16_f32 v6, v4, v5
	v_add_f32_e32 v2, v2, v3
	v_lshl_add_u64 v[4:5], s[28:29], 0, v[14:15]
	global_store_dword v[4:5], v6, off
	v_add_f32_dpp v2, v2, v2 quad_perm:[1,0,3,2] row_mask:0xf bank_mask:0xf bound_ctrl:1
	s_nop 1
	v_add_f32_dpp v2, v2, v2 quad_perm:[2,3,0,1] row_mask:0xf bank_mask:0xf bound_ctrl:1
	s_nop 1
	v_add_f32_dpp v2, v2, v2 row_half_mirror row_mask:0xf bank_mask:0xf bound_ctrl:1
	s_nop 1
	v_add_f32_dpp v2, v2, v2 row_ror:8 row_mask:0xf bank_mask:0xf bound_ctrl:1
	ds_bpermute_b32 v3, v43, v2
	s_and_saveexec_b64 s[4:5], vcc
	s_cbranch_execz .LBB0_919
	v_readlane_b32 s12, v252, 4
	v_lshlrev_b64 v[0:1], 6, v[0:1]
	v_readlane_b32 s13, v252, 5
	s_lshl_b32 s92, s9, 2
	s_waitcnt lgkmcnt(0)
	v_add_f32_e32 v2, v2, v3
	v_lshl_add_u64 v[0:1], s[12:13], 0, v[0:1]
	v_lshl_add_u64 v[0:1], v[0:1], 0, s[92:93]
	global_store_dword v[0:1], v2, off
	s_branch .LBB0_919
